# grid barrier: acquire invalidate (buffer_inv sc1) issued at arrival right after the arrive atomic instead of after the release is observed; L1 stays clean while spinning, last arriver of each XCD inva
# speedup vs baseline: 1.1213x; 1.0146x over previous
.LBB0_91:
	s_lshl_b32 s8, s33, 8
	s_mov_b64 s[10:11], exec
	s_add_u32 s8, s6, s8
	s_addc_u32 s9, s7, 0
	v_mbcnt_lo_u32_b32 v1, s10, 0
	s_add_u32 s8, s8, 0xf02e000
	v_mbcnt_hi_u32_b32 v1, s11, v1
	s_addc_u32 s9, s9, 0
	v_cmp_eq_u32_e32 vcc, 0, v1
	s_and_saveexec_b64 s[12:13], vcc
	s_cbranch_execz .LBB0_93
	s_bcnt1_i32_b64 s10, s[10:11]
	v_mov_b32_e32 v3, 0x1000
	v_mov_b32_e32 v4, s10
	global_atomic_add v3, v3, v4, s[8:9] offset:1024 sc0
	buffer_inv sc1
.LBB0_93:
	s_or_b64 exec, exec, s[12:13]
	v_cvt_f32_u32_e32 v4, v2
	s_waitcnt vmcnt(1)
	v_readfirstlane_b32 s10, v3
	v_sub_u32_e32 v3, 0, v2
	v_rcp_iflag_f32_e32 v4, v4
	v_add_u32_e32 v5, s10, v1
	v_mul_f32_e32 v4, 0x4f7ffffe, v4
	v_cvt_u32_f32_e32 v4, v4
	v_mul_lo_u32 v1, v3, v4
	v_mul_hi_u32 v1, v4, v1
	v_add_u32_e32 v1, v4, v1
	v_mul_hi_u32 v1, v5, v1
	v_mul_lo_u32 v3, v1, v2
	v_sub_u32_e32 v3, v5, v3
	v_add_u32_e32 v4, 1, v1
	v_cmp_ge_u32_e32 vcc, v3, v2
	s_nop 1
	v_cndmask_b32_e32 v1, v1, v4, vcc
	v_sub_u32_e32 v4, v3, v2
	v_cndmask_b32_e32 v3, v3, v4, vcc
	v_add_u32_e32 v4, 1, v1
	v_cmp_ge_u32_e32 vcc, v3, v2
	v_add_u32_e32 v3, 1, v5
	s_nop 0
	v_cndmask_b32_e32 v1, v1, v4, vcc
	v_mul_lo_u32 v4, v2, v1
	v_add_u32_e32 v2, v4, v2
	v_cmp_ne_u32_e32 vcc, v3, v2
	s_and_saveexec_b64 s[10:11], vcc
	s_xor_b64 s[10:11], exec, s[10:11]
	s_cbranch_execz .LBB0_107
	s_waitcnt lgkmcnt(0)
	v_mov_b32_e32 v0, 0x2000
	global_load_dword v0, v0, s[8:9] offset:1024 sc1
	s_add_u32 s16, s8, 0x2400
	s_addc_u32 s17, s9, 0
	s_waitcnt vmcnt(0)
	v_cmp_eq_u32_e32 vcc, v0, v1
	s_and_saveexec_b64 s[12:13], vcc
	s_cbranch_execz .LBB0_106
	s_add_u32 s14, s6, 0xf02e200
	s_addc_u32 s15, s7, 0
	s_mov_b32 s28, 1
	s_mov_b64 s[18:19], 0
	v_mov_b32_e32 v0, 0
	s_branch .LBB0_97

.LBB0_106:
	s_or_b64 exec, exec, s[12:13]
	s_waitcnt vmcnt(0)
	s_waitcnt vmcnt(0)

.LBB0_124:
	s_or_b64 exec, exec, s[6:7]
	s_mov_b64 s[6:7], exec
	v_mbcnt_lo_u32_b32 v0, s6, 0
	v_mbcnt_hi_u32_b32 v0, s7, v0
	v_cmp_eq_u32_e32 vcc, 0, v0
	s_waitcnt vmcnt(0)
	s_and_saveexec_b64 s[10:11], vcc
	s_cbranch_execz .LBB0_126
	s_bcnt1_i32_b64 s6, s[6:7]
	v_mov_b32_e32 v0, 0x2000
	v_mov_b32_e32 v1, s6
	global_atomic_add v0, v1, s[8:9] offset:1024

.LBB0_505:
	s_lshl_b32 s4, s4, 8
	s_mov_b64 s[10:11], exec
	s_add_u32 s4, s24, s4
	s_addc_u32 s12, s25, 0
	v_mbcnt_lo_u32_b32 v1, s10, 0
	s_add_u32 s26, s4, 0xf02e000
	v_mbcnt_hi_u32_b32 v1, s11, v1
	s_addc_u32 s27, s12, 0
	v_cmp_eq_u32_e32 vcc, 0, v1
	s_and_saveexec_b64 s[12:13], vcc
	s_cbranch_execz .LBB0_507
	s_bcnt1_i32_b64 s4, s[10:11]
	v_mov_b32_e32 v3, s4
	global_atomic_add v3, v240, v3, s[26:27] offset:1024 sc0
	buffer_inv sc1
.LBB0_507:
	s_or_b64 exec, exec, s[12:13]
	v_cvt_f32_u32_e32 v4, v2
	s_waitcnt vmcnt(1)
	v_readfirstlane_b32 s4, v3
	v_sub_u32_e32 v3, 0, v2
	v_rcp_iflag_f32_e32 v4, v4
	v_add_u32_e32 v5, s4, v1
	v_mul_f32_e32 v4, 0x4f7ffffe, v4
	v_cvt_u32_f32_e32 v4, v4
	v_mul_lo_u32 v1, v3, v4
	v_mul_hi_u32 v1, v4, v1
	v_add_u32_e32 v1, v4, v1
	v_mul_hi_u32 v1, v5, v1
	v_mul_lo_u32 v3, v1, v2
	v_sub_u32_e32 v3, v5, v3
	v_add_u32_e32 v4, 1, v1
	v_cmp_ge_u32_e32 vcc, v3, v2
	s_nop 1
	v_cndmask_b32_e32 v1, v1, v4, vcc
	v_sub_u32_e32 v4, v3, v2
	v_cndmask_b32_e32 v3, v3, v4, vcc
	v_add_u32_e32 v4, 1, v1
	v_cmp_ge_u32_e32 vcc, v3, v2
	v_add_u32_e32 v3, 1, v5
	s_nop 0
	v_cndmask_b32_e32 v1, v1, v4, vcc
	v_mul_lo_u32 v4, v2, v1
	v_add_u32_e32 v2, v4, v2
	v_cmp_ne_u32_e32 vcc, v3, v2
	s_and_saveexec_b64 s[10:11], vcc
	s_xor_b64 s[10:11], exec, s[10:11]
	s_cbranch_execz .LBB0_521
	s_waitcnt lgkmcnt(0)
	v_mov_b32_e32 v0, 0x2000
	global_load_dword v0, v0, s[26:27] offset:1024 sc1
	s_add_u32 s28, s26, 0x2400
	s_addc_u32 s29, s27, 0
	s_waitcnt vmcnt(0)
	v_cmp_eq_u32_e32 vcc, v0, v1
	s_and_saveexec_b64 s[12:13], vcc
	s_cbranch_execz .LBB0_520
	s_add_u32 s16, s24, 0xf02e200
	s_addc_u32 s17, s25, 0
	s_mov_b32 s4, 1
	s_mov_b64 s[30:31], 0
	s_branch .LBB0_511

.LBB0_538:
	s_or_b64 exec, exec, s[10:11]
	s_mov_b64 s[10:11], exec
	v_mbcnt_lo_u32_b32 v0, s10, 0
	v_mbcnt_hi_u32_b32 v0, s11, v0
	v_cmp_eq_u32_e32 vcc, 0, v0
	s_waitcnt vmcnt(0)
	s_and_saveexec_b64 s[12:13], vcc
	s_cbranch_execz .LBB0_540
	s_bcnt1_i32_b64 s4, s[10:11]
	v_mov_b32_e32 v0, s4
	v_mov_b32_e32 v1, 0x2000
	global_atomic_add v1, v0, s[26:27] offset:1024

.LBB0_1115:
	s_lshl_b32 s4, s4, 8
	s_mov_b64 s[10:11], exec
	s_add_u32 s4, s30, s4
	s_addc_u32 s12, s31, 0
	v_mbcnt_lo_u32_b32 v1, s10, 0
	s_add_u32 s34, s4, 0xf02e000
	v_mbcnt_hi_u32_b32 v1, s11, v1
	s_addc_u32 s35, s12, 0
	v_cmp_eq_u32_e32 vcc, 0, v1
	s_and_saveexec_b64 s[12:13], vcc
	s_cbranch_execz .LBB0_1117
	s_bcnt1_i32_b64 s4, s[10:11]
	v_mov_b32_e32 v3, s4
	global_atomic_add v3, v240, v3, s[34:35] offset:1024 sc0
	buffer_inv sc1
.LBB0_1117:
	s_or_b64 exec, exec, s[12:13]
	v_cvt_f32_u32_e32 v4, v2
	s_waitcnt vmcnt(1)
	v_readfirstlane_b32 s4, v3
	v_sub_u32_e32 v3, 0, v2
	v_rcp_iflag_f32_e32 v4, v4
	v_add_u32_e32 v5, s4, v1
	v_mul_f32_e32 v4, 0x4f7ffffe, v4
	v_cvt_u32_f32_e32 v4, v4
	v_mul_lo_u32 v1, v3, v4
	v_mul_hi_u32 v1, v4, v1
	v_add_u32_e32 v1, v4, v1
	v_mul_hi_u32 v1, v5, v1
	v_mul_lo_u32 v3, v1, v2
	v_sub_u32_e32 v3, v5, v3
	v_add_u32_e32 v4, 1, v1
	v_cmp_ge_u32_e32 vcc, v3, v2
	s_nop 1
	v_cndmask_b32_e32 v1, v1, v4, vcc
	v_sub_u32_e32 v4, v3, v2
	v_cndmask_b32_e32 v3, v3, v4, vcc
	v_add_u32_e32 v4, 1, v1
	v_cmp_ge_u32_e32 vcc, v3, v2
	v_add_u32_e32 v3, 1, v5
	s_nop 0
	v_cndmask_b32_e32 v1, v1, v4, vcc
	v_mul_lo_u32 v4, v2, v1
	v_add_u32_e32 v2, v4, v2
	v_cmp_ne_u32_e32 vcc, v3, v2
	s_and_saveexec_b64 s[10:11], vcc
	s_xor_b64 s[10:11], exec, s[10:11]
	s_cbranch_execz .LBB0_1131
	s_waitcnt lgkmcnt(0)
	v_mov_b32_e32 v0, 0x2000
	global_load_dword v0, v0, s[34:35] offset:1024 sc1
	s_add_u32 s36, s34, 0x2400
	s_addc_u32 s37, s35, 0
	s_waitcnt vmcnt(0)
	v_cmp_eq_u32_e32 vcc, v0, v1
	s_and_saveexec_b64 s[12:13], vcc
	s_cbranch_execz .LBB0_1130
	s_add_u32 s16, s30, 0xf02e200
	s_addc_u32 s17, s31, 0
	s_mov_b32 s4, 1
	s_mov_b64 s[38:39], 0
	s_branch .LBB0_1121

.LBB0_1148:
	s_or_b64 exec, exec, s[10:11]
	s_mov_b64 s[10:11], exec
	v_mbcnt_lo_u32_b32 v0, s10, 0
	v_mbcnt_hi_u32_b32 v0, s11, v0
	v_cmp_eq_u32_e32 vcc, 0, v0
	s_waitcnt vmcnt(0)
	s_and_saveexec_b64 s[12:13], vcc
	s_cbranch_execz .LBB0_1150
	s_bcnt1_i32_b64 s4, s[10:11]
	v_mov_b32_e32 v0, s4
	v_mov_b32_e32 v1, 0x2000
	global_atomic_add v1, v0, s[34:35] offset:1024

.LBB0_1427:
	s_or_b64 exec, exec, s[10:11]
	s_mov_b64 s[10:11], exec
	v_mbcnt_lo_u32_b32 v0, s10, 0
	v_mbcnt_hi_u32_b32 v0, s11, v0
	v_cmp_eq_u32_e32 vcc, 0, v0
	s_waitcnt vmcnt(0)
	s_and_saveexec_b64 s[12:13], vcc
	s_cbranch_execnz .LBB0_1428
	s_getpc_b64 s[98:99]
